# P1: filter FFTs on workgroups 0..127, first RMS-norm on 128..255, run side by side
# speedup vs baseline: 1.0069x; 1.0069x over previous
; #define LAS __attribute__((address_space(3)))
; __device__ __forceinline__ void filter_phase(LAS unsigned char* L, const Args& a) {
;     ...
;     for (int pair = blockIdx.x; pair < 512; pair += gridDim.x) {
;         const int ca = 2 * pair;
;         {
;             LAS bf16_t* WTt = (LAS bf16_t*)WT;
;             for (int idx = tid; idx < 1024; idx += 512) { const int n = idx >> 6, k = idx & 63;
;                 const float v = (n < 4) ? wout[(size_t)k * 2048 + ((n & 2) ? 1024 : 0) + ca + (n & 1)] : 0.f; WTt[idx] = (bf16_t)(pk2(v, 0.f) & 0xffffu); }
;         }
;         __syncthreads();
;         const float da = fabsf(decay[ca]), db = fabsf(decay[ca + 1]);
;         float sa = 0.f, sb = 0.f;
;         {
;             const int lane = tid & 63, w = tid >> 6, n = lane & 15, q = lane >> 4;
;             const bf16x8 b0 = *(const LAS bf16x8*)((const LAS bf16_t*)WT + n * 64 + 8 * q), b1 = *(const LAS bf16x8*)((const LAS bf16_t*)WT + n * 64 + 32 + 8 * q);
;             const float dsel = (n & 1) ? db : da; float ssum = 0.f;
;             LAS float* zf = (LAS float*)z;
; #pragma unroll 1
;             for (int mg = 0; mg < 4; ++mg) {
;             bf16x8 a0v[16], a1v[16];
; #pragma unroll
;             for (int u = 0; u < 16; ++u) { const bf16_t* hp = HDN + (size_t)(16 * (w + 8 * (mg * 16 + u)) + n) * 64 + 8 * q; a0v[u] = *(const bf16x8*)hp; a1v[u] = *(const bf16x8*)(hp + 32); }
; #pragma unroll
;             for (int u = 0; u < 16; ++u) {
;                 const int mt = w + 8 * (mg * 16 + u); const int m0 = 16 * mt; const bf16x8 a0 = a0v[u], a1 = a1v[u];
;                 f32x4 acc = {0.f, 0.f, 0.f, 0.f};
;                 acc = __builtin_amdgcn_mfma_f32_16x16x32_bf16(a0, b0, acc, 0, 0, 0); acc = __builtin_amdgcn_mfma_f32_16x16x32_bf16(a1, b1, acc, 0, 0, 0);
;                 {
;                     const int ml = lane >> 2, nn = lane & 3, src = nn + 16 * (ml >> 2);
;                     const float v0 = __shfl(acc[0], src), v1 = __shfl(acc[1], src), v2 = __shfl(acc[2], src), v3 = __shfl(acc[3], src);
;                     const int isel = ml & 3; float v = isel == 0 ? v0 : isel == 1 ? v1 : isel == 2 ? v2 : v3;
;                     const int m = m0 + ml; const float t = (float)m / (float)(SEQ - 1); v *= expf(-t * ((nn & 1) ? db : da));
;                     if (nn < 2) { zf[2 * PH(m) + nn] = v; ssum += fabsf(v); }
.LBB0_124:
	s_or_b64 exec, exec, s[8:9]
	s_movk_i32 s23, 0x1ff
	s_lshr_b32 s97, s3, 1
	s_cmp_ge_i32 s2, s97
	v_and_b32_e32 v153, 63, v152
	v_lshrrev_b32_e32 v133, 6, v152
	v_mov_b32_e32 v129, 0
	s_waitcnt lgkmcnt(0)
	s_barrier
	s_cbranch_scc1 .LBB0_313
	s_add_u32 s25, s28, 0x3600000
	s_addc_u32 s70, s29, 0
	s_add_u32 s71, s28, 0x80000
	s_addc_u32 s72, s29, 0
	s_add_i32 s73, 0, 0x20400
	v_and_b32_e32 v2, 1, v152
	v_lshl_add_u32 v158, v0, 3, s73
	v_and_b32_e32 v0, 56, v153
	s_add_i32 s24, 0, 0x20000
	v_cmp_eq_u32_e64 s[0:1], 0, v2
	v_add_u32_e32 v160, s24, v0
	v_and_b32_e32 v2, 0xf0, v152
	v_lshlrev_b32_e32 v4, 8, v152
	s_movk_i32 s24, 0xf00
	v_and_or_b32 v11, v4, s24, v2
	v_and_b32_e32 v2, 1, v133
	v_lshlrev_b32_e32 v0, 7, v152
	v_lshlrev_b32_e32 v128, 2, v2
	v_lshrrev_b32_e32 v2, 8, v152
	v_and_b32_e32 v0, 0x380, v0
	v_or_b32_e32 v2, v11, v2
	v_add_u32_e32 v161, s73, v0
	v_lshlrev_b32_e32 v164, 2, v152
	v_lshrrev_b32_e32 v0, 2, v152
	v_sub_u32_e32 v4, 0, v2
	v_and_b32_e32 v165, 60, v0
	v_lshlrev_b32_e32 v6, 10, v4
	v_lshrrev_b32_e32 v10, 6, v4
	v_bitop3_b32 v0, v0, v164, 60 bitop3:0x6c
	v_and_b32_e32 v6, 0x3c00, v6
	v_lshlrev_b32_e32 v8, 2, v4
	v_and_b32_e32 v10, 60, v10
	v_bfe_u32 v12, v4, 12, 2
	v_lshl_add_u32 v167, v0, 3, 0
	v_lshrrev_b32_e32 v0, 2, v4
	v_and_b32_e32 v8, 0x3c0, v8
	v_or3_b32 v6, v12, v10, v6
	v_and_b32_e32 v0, 60, v0
	v_sub_u32_e32 v2, 0x3000, v2
	v_bitop3_b32 v0, v6, v0, v8 bitop3:0x36
	v_lshlrev_b32_e32 v10, 10, v2
	v_lshlrev_b32_e32 v12, 2, v2
	v_lshrrev_b32_e32 v13, 6, v2
	v_lshrrev_b32_e32 v14, 12, v2
	v_lshl_add_u32 v168, v0, 3, 0
	v_lshrrev_b32_e32 v0, 2, v2
	v_add_u32_e32 v2, 0x200, v152
	v_lshrrev_b32_e32 v4, 8, v2
	v_and_b32_e32 v10, 0x3c00, v10
	v_and_b32_e32 v13, 60, v13
	v_or_b32_e32 v4, v11, v4
	v_and_b32_e32 v12, 0x3c0, v12
	v_or3_b32 v10, v13, v14, v10
	v_and_b32_e32 v0, 60, v0
	v_sub_u32_e32 v6, 0, v4
	v_bitop3_b32 v0, v10, v0, v12 bitop3:0x36
	v_lshlrev_b32_e32 v8, 10, v6
	v_lshlrev_b32_e32 v10, 2, v6
	v_lshrrev_b32_e32 v12, 6, v6
	v_and_b32_e32 v8, 0x3c00, v8
	v_and_b32_e32 v10, 0x3c0, v10
	v_and_b32_e32 v12, 60, v12
	v_sub_u32_e32 v4, 0x3000, v4
	v_or3_b32 v8, v12, v8, v10
	v_lshrrev_b32_e32 v10, 6, v4
	v_lshlrev_b32_e32 v12, 2, v4
	v_lshl_or_b32 v10, v4, 10, v10
	v_and_b32_e32 v12, 0x3c0, v12
	s_movk_i32 s24, 0x3c3c
	v_lshrrev_b32_e32 v4, 2, v4
	v_and_or_b32 v10, v10, s24, v12
	v_lshrrev_b32_e32 v6, 2, v6
	v_and_b32_e32 v4, 60, v4
	v_and_b32_e32 v6, 60, v6
	v_bitop3_b32 v4, v10, v4, 2 bitop3:0x36
	v_bitop3_b32 v6, v8, v6, 3 bitop3:0x36
	v_lshl_add_u32 v172, v4, 3, 0
	v_or_b32_e32 v4, 0x400, v152
	v_lshl_add_u32 v171, v6, 3, 0
	v_lshrrev_b32_e32 v6, 8, v4
	v_or_b32_e32 v6, v11, v6
	v_lshlrev_b32_e32 v12, 5, v2
	v_lshlrev_b32_e32 v13, 3, v165
	v_sub_u32_e32 v8, 0, v6
	v_xad_u32 v170, v12, v13, 0
	v_lshlrev_b32_e32 v10, 10, v8
	v_lshlrev_b32_e32 v12, 2, v8
	v_lshrrev_b32_e32 v14, 6, v8
	v_and_b32_e32 v10, 0x3c00, v10
	v_and_b32_e32 v12, 0x3c0, v12
	v_and_b32_e32 v14, 60, v14
	v_sub_u32_e32 v6, 0x3000, v6
	v_or3_b32 v10, v14, v10, v12
	v_lshrrev_b32_e32 v12, 6, v6
	v_lshlrev_b32_e32 v14, 2, v6
	v_lshl_or_b32 v12, v6, 10, v12
	v_and_b32_e32 v14, 0x3c0, v14
	v_lshrrev_b32_e32 v6, 2, v6
	v_and_or_b32 v12, v12, s24, v14
	v_lshrrev_b32_e32 v8, 2, v8
	v_and_b32_e32 v6, 60, v6
	v_and_b32_e32 v8, 60, v8
	v_bitop3_b32 v6, v12, v6, 2 bitop3:0x36
	v_bitop3_b32 v8, v10, v8, 3 bitop3:0x36
	v_lshl_add_u32 v175, v6, 3, 0
	v_add_u32_e32 v6, 0x600, v152
	v_lshl_add_u32 v174, v8, 3, 0
	v_lshrrev_b32_e32 v8, 8, v6
	v_or_b32_e32 v8, v11, v8
	v_lshlrev_b32_e32 v14, 5, v4
	v_sub_u32_e32 v10, 0, v8
	v_xad_u32 v173, v14, v13, 0
	v_lshlrev_b32_e32 v12, 10, v10
	v_lshlrev_b32_e32 v14, 2, v10
	v_lshrrev_b32_e32 v15, 6, v10
	v_and_b32_e32 v12, 0x3c00, v12
	v_and_b32_e32 v14, 0x3c0, v14
	v_and_b32_e32 v15, 60, v15
	v_sub_u32_e32 v8, 0x3000, v8
	v_or3_b32 v12, v15, v12, v14
	v_lshrrev_b32_e32 v14, 6, v8
	v_lshlrev_b32_e32 v15, 2, v8
	v_lshl_or_b32 v14, v8, 10, v14
	v_and_b32_e32 v15, 0x3c0, v15
	v_lshrrev_b32_e32 v8, 2, v8
	v_and_or_b32 v14, v14, s24, v15
	v_lshrrev_b32_e32 v10, 2, v10
	v_and_b32_e32 v8, 60, v8
	v_and_b32_e32 v10, 60, v10
	v_bitop3_b32 v8, v14, v8, 2 bitop3:0x36
	v_bitop3_b32 v10, v12, v10, 3 bitop3:0x36
	v_lshl_add_u32 v178, v8, 3, 0
	v_or_b32_e32 v8, 0x800, v152
	v_lshl_add_u32 v177, v10, 3, 0
	v_lshrrev_b32_e32 v10, 8, v8
	v_or_b32_e32 v10, v11, v10
	v_lshlrev_b32_e32 v15, 5, v6
	v_sub_u32_e32 v12, 0, v10
	v_xad_u32 v176, v15, v13, 0
	v_lshlrev_b32_e32 v14, 10, v12
	v_lshlrev_b32_e32 v15, 2, v12
	v_lshrrev_b32_e32 v16, 6, v12
	v_and_b32_e32 v14, 0x3c00, v14
	v_and_b32_e32 v15, 0x3c0, v15
	v_and_b32_e32 v16, 60, v16
	v_sub_u32_e32 v10, 0x3000, v10
	v_or3_b32 v14, v16, v14, v15
	v_lshrrev_b32_e32 v15, 6, v10
	v_lshlrev_b32_e32 v16, 2, v10
	v_lshl_or_b32 v15, v10, 10, v15
	v_and_b32_e32 v16, 0x3c0, v16
	v_lshrrev_b32_e32 v10, 2, v10
	v_and_or_b32 v15, v15, s24, v16
	v_lshrrev_b32_e32 v12, 2, v12
	v_and_b32_e32 v10, 60, v10
	v_and_b32_e32 v12, 60, v12
	v_bitop3_b32 v10, v15, v10, 2 bitop3:0x36
	v_bitop3_b32 v12, v14, v12, 3 bitop3:0x36
	v_lshl_add_u32 v181, v10, 3, 0
	v_add_u32_e32 v10, 0xa00, v152
	v_lshl_add_u32 v180, v12, 3, 0
	v_lshrrev_b32_e32 v12, 8, v10
	v_or_b32_e32 v12, v11, v12
	v_lshlrev_b32_e32 v16, 5, v8
	v_sub_u32_e32 v14, 0, v12
	v_xad_u32 v179, v16, v13, 0
	v_lshlrev_b32_e32 v15, 10, v14
	v_lshlrev_b32_e32 v16, 2, v14
	v_lshrrev_b32_e32 v17, 6, v14
	v_and_b32_e32 v15, 0x3c00, v15
	v_and_b32_e32 v16, 0x3c0, v16
	v_and_b32_e32 v17, 60, v17
	v_sub_u32_e32 v12, 0x3000, v12
	v_or3_b32 v15, v17, v15, v16
	v_lshrrev_b32_e32 v16, 6, v12
	v_lshlrev_b32_e32 v17, 2, v12
	v_lshl_or_b32 v16, v12, 10, v16
; #define LAS __attribute__((address_space(3)))
; __device__ __forceinline__ void filter_phase(LAS unsigned char* L, const Args& a) {
;     ...
;     for (int pair = blockIdx.x; pair < 512; pair += gridDim.x) {
;         const int ca = 2 * pair;
;         {
;             LAS bf16_t* WTt = (LAS bf16_t*)WT;
;             for (int idx = tid; idx < 1024; idx += 512) { const int n = idx >> 6, k = idx & 63;
;                 const float v = (n < 4) ? wout[(size_t)k * 2048 + ((n & 2) ? 1024 : 0) + ca + (n & 1)] : 0.f; WTt[idx] = (bf16_t)(pk2(v, 0.f) & 0xffffu); }
;         }
;         __syncthreads();
;         const float da = fabsf(decay[ca]), db = fabsf(decay[ca + 1]);
;         float sa = 0.f, sb = 0.f;
;         {
;             const int lane = tid & 63, w = tid >> 6, n = lane & 15, q = lane >> 4;
;             const bf16x8 b0 = *(const LAS bf16x8*)((const LAS bf16_t*)WT + n * 64 + 8 * q), b1 = *(const LAS bf16x8*)((const LAS bf16_t*)WT + n * 64 + 32 + 8 * q);
;             const float dsel = (n & 1) ? db : da; float ssum = 0.f;
;             LAS float* zf = (LAS float*)z;
; #pragma unroll 1
;             for (int mg = 0; mg < 4; ++mg) {
;             bf16x8 a0v[16], a1v[16];
; #pragma unroll
;             for (int u = 0; u < 16; ++u) { const bf16_t* hp = HDN + (size_t)(16 * (w + 8 * (mg * 16 + u)) + n) * 64 + 8 * q; a0v[u] = *(const bf16x8*)hp; a1v[u] = *(const bf16x8*)(hp + 32); }
; #pragma unroll
;             for (int u = 0; u < 16; ++u) {
;                 const int mt = w + 8 * (mg * 16 + u); const int m0 = 16 * mt; const bf16x8 a0 = a0v[u], a1 = a1v[u];
;                 f32x4 acc = {0.f, 0.f, 0.f, 0.f};
;                 acc = __builtin_amdgcn_mfma_f32_16x16x32_bf16(a0, b0, acc, 0, 0, 0); acc = __builtin_amdgcn_mfma_f32_16x16x32_bf16(a1, b1, acc, 0, 0, 0);
;                 {
;                     const int ml = lane >> 2, nn = lane & 3, src = nn + 16 * (ml >> 2);
;                     const float v0 = __shfl(acc[0], src), v1 = __shfl(acc[1], src), v2 = __shfl(acc[2], src), v3 = __shfl(acc[3], src);
;                     const int isel = ml & 3; float v = isel == 0 ? v0 : isel == 1 ? v1 : isel == 2 ? v2 : v3;
;                     const int m = m0 + ml; const float t = (float)m / (float)(SEQ - 1); v *= expf(-t * ((nn & 1) ? db : da));
;                     if (nn < 2) { zf[2 * PH(m) + nn] = v; ssum += fabsf(v); }
	v_and_b32_e32 v17, 0x3c0, v17
	v_lshrrev_b32_e32 v12, 2, v12
	v_and_or_b32 v16, v16, s24, v17
	v_lshrrev_b32_e32 v14, 2, v14
	v_and_b32_e32 v12, 60, v12
	v_and_b32_e32 v14, 60, v14
	v_bitop3_b32 v12, v16, v12, 2 bitop3:0x36
	v_bitop3_b32 v14, v15, v14, 3 bitop3:0x36
	v_lshl_add_u32 v184, v12, 3, 0
	v_or_b32_e32 v12, 0xc00, v152
	v_lshl_add_u32 v183, v14, 3, 0
	v_lshrrev_b32_e32 v14, 8, v12
	v_or_b32_e32 v14, v11, v14
	v_lshlrev_b32_e32 v17, 5, v10
	v_sub_u32_e32 v15, 0, v14
	v_xad_u32 v182, v17, v13, 0
	v_lshlrev_b32_e32 v16, 10, v15
	v_lshlrev_b32_e32 v17, 2, v15
	v_lshrrev_b32_e32 v18, 6, v15
	v_and_b32_e32 v16, 0x1c00, v16
	v_and_b32_e32 v17, 0x3c0, v17
	v_and_b32_e32 v18, 60, v18
	v_sub_u32_e32 v14, 0x3000, v14
	v_or3_b32 v16, v18, v16, v17
	v_lshrrev_b32_e32 v17, 6, v14
	v_lshlrev_b32_e32 v18, 2, v14
	v_lshl_or_b32 v17, v14, 10, v17
	v_and_b32_e32 v18, 0x3c0, v18
	s_movk_i32 s33, 0x1c3c
	v_lshrrev_b32_e32 v14, 2, v14
	v_and_or_b32 v17, v17, s33, v18
	v_lshrrev_b32_e32 v15, 2, v15
	v_and_b32_e32 v14, 60, v14
	v_and_b32_e32 v15, 60, v15
	v_bitop3_b32 v14, v17, v14, 2 bitop3:0x36
	v_bitop3_b32 v15, v16, v15, 3 bitop3:0x36
	v_lshl_add_u32 v187, v14, 3, 0
	v_add_u32_e32 v14, 0xe00, v152
	v_lshl_add_u32 v186, v15, 3, 0
	v_lshrrev_b32_e32 v15, 8, v14
	v_or_b32_e32 v11, v11, v15
	v_lshlrev_b32_e32 v18, 5, v12
	v_sub_u32_e32 v15, 0, v11
	v_xad_u32 v185, v18, v13, 0
	v_lshlrev_b32_e32 v16, 10, v15
	v_lshlrev_b32_e32 v17, 2, v15
	v_lshrrev_b32_e32 v18, 6, v15
	v_and_b32_e32 v16, 0x3c00, v16
	v_and_b32_e32 v17, 0x3c0, v17
	v_and_b32_e32 v18, 60, v18
	v_sub_u32_e32 v11, 0x3000, v11
	v_or3_b32 v16, v18, v16, v17
	v_lshrrev_b32_e32 v17, 6, v11
	v_lshlrev_b32_e32 v18, 2, v11
	v_lshl_or_b32 v17, v11, 10, v17
	v_and_b32_e32 v18, 0x3c0, v18
	v_lshrrev_b32_e32 v11, 2, v11
	v_and_or_b32 v17, v17, s24, v18
	v_lshlrev_b32_e32 v18, 5, v14
	v_and_b32_e32 v11, 60, v11
	v_xad_u32 v188, v18, v13, 0
	v_lshrrev_b32_e32 v13, 2, v15
	v_bitop3_b32 v11, v17, v11, 2 bitop3:0x36
	v_and_b32_e32 v13, 60, v13
	v_lshl_add_u32 v190, v11, 3, 0
	v_mbcnt_lo_u32_b32 v11, -1, 0
	v_bitop3_b32 v13, v16, v13, 3 bitop3:0x36
	v_mbcnt_hi_u32_b32 v11, -1, v11
	v_lshl_add_u32 v189, v13, 3, 0
	v_and_b32_e32 v13, 64, v11
	v_and_or_b32 v15, v152, 51, v13
	v_lshlrev_b32_e32 v191, 2, v15
	v_add_u32_e32 v13, 64, v13
	v_xor_b32_e32 v15, 1, v11
	v_cmp_lt_i32_e32 vcc, v15, v13
	v_lshrrev_b32_e32 v5, 2, v153
	v_and_b32_e32 v1, 15, v152
	v_cndmask_b32_e32 v15, v11, v15, vcc
	v_lshlrev_b32_e32 v192, 2, v15
	v_xor_b32_e32 v15, 2, v11
	v_cmp_lt_i32_e32 vcc, v15, v13
	v_lshl_or_b32 v5, v133, 4, v5
	v_lshlrev_b32_e32 v1, 7, v1
	v_cndmask_b32_e32 v15, v11, v15, vcc
	v_lshlrev_b32_e32 v193, 2, v15
	v_xor_b32_e32 v15, 4, v11
	v_cmp_lt_i32_e32 vcc, v15, v13
	s_add_i32 s22, 0, 0x20800
	v_and_b32_e32 v3, 48, v152
	v_cndmask_b32_e32 v15, v11, v15, vcc
	v_lshlrev_b32_e32 v194, 2, v15
	v_xor_b32_e32 v15, 8, v11
	v_cmp_lt_i32_e32 vcc, v15, v13
	v_lshl_add_u32 v169, v0, 3, 0
	v_lshlrev_b32_e32 v0, 1, v152
	v_cndmask_b32_e32 v15, v11, v15, vcc
	v_lshlrev_b32_e32 v195, 2, v15
	v_xor_b32_e32 v15, 16, v11
	v_cmp_lt_i32_e32 vcc, v15, v13
	v_add_u32_e32 v202, 0x780, v5
	v_sub_u32_e32 v203, 0x3880, v5
	v_cndmask_b32_e32 v15, v11, v15, vcc
	v_lshlrev_b32_e32 v196, 2, v15
	v_xor_b32_e32 v15, 32, v11
	v_cmp_lt_i32_e32 vcc, v15, v13
	v_lshlrev_b32_e32 v5, 5, v152
	v_add3_u32 v154, s22, v1, v3
	v_cndmask_b32_e32 v11, v11, v15, vcc
	v_lshlrev_b32_e32 v197, 2, v11
	v_add_u32_e32 v200, s22, v0
	s_movk_i32 s22, 0x780
	v_and_b32_e32 v5, 0x7800, v5
	v_lshlrev_b32_e32 v11, 5, v153
	v_and_or_b32 v132, v11, s22, v5
	v_lshlrev_b32_e32 v5, 11, v133
	v_lshl_add_u64 v[130:131], s[82:83], 0, v[128:129]
	v_or3_b32 v128, v5, v1, v3
	v_add_u32_e32 v16, 0x4000, v128
	v_mov_b32_e32 v17, v129
	v_lshl_add_u64 v[136:137], s[28:29], 0, v[16:17]
	v_add_u32_e32 v16, 0xc000, v128
	v_lshl_add_u64 v[138:139], s[28:29], 0, v[16:17]
	v_add_u32_e32 v16, 0x14000, v128
	v_lshl_add_u64 v[140:141], s[28:29], 0, v[16:17]
	v_add_u32_e32 v16, 0x1c000, v128
	v_and_b32_e32 v155, 3, v152
	v_lshlrev_b32_e32 v7, 3, v133
	v_lshl_add_u64 v[142:143], s[28:29], 0, v[16:17]
	v_add_u32_e32 v16, 0x24000, v128
	v_lshlrev_b32_e32 v9, 4, v155
	v_lshl_add_u64 v[144:145], s[28:29], 0, v[16:17]
	v_add_u32_e32 v16, 0x2c000, v128
	v_add_u32_e32 v1, 0, v7
	v_bfe_u32 v156, v153, 2, 2
	v_and_b32_e32 v162, 60, v152
	v_lshlrev_b32_e32 v2, 1, v2
	v_lshlrev_b32_e32 v4, 1, v4
	v_lshlrev_b32_e32 v6, 1, v6
	v_lshlrev_b32_e32 v8, 1, v8
	v_lshlrev_b32_e32 v10, 1, v10
	v_lshlrev_b32_e32 v12, 1, v12
	v_lshlrev_b32_e32 v14, 1, v14
	v_lshl_add_u64 v[134:135], s[28:29], 0, v[128:129]
	v_lshl_add_u64 v[146:147], s[28:29], 0, v[16:17]
	v_add_u32_e32 v16, 0x34000, v128
	v_add_u32_e32 v128, 0x3c000, v128
	v_add_u32_e32 v204, 0x21000, v1
	s_mov_b32 s38, 0x3f3504f3
	s_mov_b32 s42, 0xbec3ef15
	v_add_u32_e32 v1, 0, v9
	s_mov_b32 s44, 0.5
	v_cmp_lt_u32_e64 s[10:11], 1, v155
	v_lshl_add_u32 v157, v155, 2, 0
	v_cmp_eq_u32_e64 s[4:5], 2, v156
	v_cmp_eq_u32_e64 s[6:7], 0, v152
	v_cmp_eq_u32_e64 s[8:9], 0, v153
	v_lshlrev_b32_e32 v159, 4, v152
	v_lshl_add_u32 v163, v162, 3, 0
	v_and_b32_e32 v166, 12, v133
	v_lshlrev_b32_e32 v198, 11, v152
	v_lshlrev_b32_e32 v199, 3, v152
	v_add_u32_e32 v201, 0x78, v133
	v_lshl_add_u64 v[148:149], s[28:29], 0, v[16:17]
	v_lshl_add_u64 v[150:151], s[28:29], 0, v[128:129]
	s_movk_i32 s74, 0x100
	s_mov_b32 s75, 0x1f800
	s_mov_b32 s76, 0x300000
	s_mov_b32 s77, 0xc5fff800
	s_mov_b32 s78, 0x3fb8aa3b
	s_mov_b32 s79, 0xc2ce8ed0
	s_mov_b32 s80, 0x42b17218
	s_add_i32 s81, 0, 0x10000
	s_add_i32 s82, 0, 0x21010
	s_add_i32 s83, 0, 0x21020
	s_add_i32 s86, 0, 0x21030
	s_mov_b32 s22, 0x3f6c835e
	s_mov_b32 s24, 0x3ec3ef15
	s_mov_b32 s39, 0xbf3504f3
	s_mov_b32 s43, 0xbf6c835e
	v_add_u32_e32 v205, 0x20000, v1
	s_movk_i32 s87, 0x7fc0
	s_mov_b32 s45, -0.5
	v_lshlrev_b32_e32 v206, 4, v0
	v_lshlrev_b32_e32 v207, 4, v2
	v_lshlrev_b32_e32 v208, 4, v4
	v_lshlrev_b32_e32 v209, 4, v6
	v_lshlrev_b32_e32 v210, 4, v8
	v_lshlrev_b32_e32 v211, 4, v10
	v_lshlrev_b32_e32 v212, 4, v12
	v_lshlrev_b32_e32 v213, 4, v14
	v_mov_b32_e32 v214, 0x7f800000
	v_mov_b32_e32 v224, v129
	v_mov_b32_e32 v225, v129
	s_mov_b32 s46, s2
	s_branch .LBB0_127
.LBB0_126:
	s_or_b64 exec, exec, s[52:53]
	s_add_i32 s46, s46, s97
	s_cmpk_lt_i32 s46, 0x200
	s_barrier
	s_cbranch_scc0 .LBB0_313

; __device__ __forceinline__ void norm_rows(const float* x, int nrows, const float* g, const float* sc, const float* sh, bf16_t* o, int lane) {
;     f32x4 gs[4], shv[4];
; #pragma unroll
;     for (int j = 0; j < 4; ++j) { const int k = 4 * lane + 256 * j; const f32x4 gg = *(const f32x4*)(g + k), s = *(const f32x4*)(sc + k); gs[j] = gg * (1.0f + s); shv[j] = *(const f32x4*)(sh + k); }
;     int r0 = 0;
; #pragma unroll 1
;     for (; r0 + 4 <= nrows; r0 += 4) {
; __device__ __forceinline__ void norm_phase(const Args& a, const float* x, int layer, int which  , bool with_ctx) {
;     const int tid = threadIdx.x, lane = tid & 63, w = tid >> 6; const int gw = blockIdx.x * 8 + w, NGW = gridDim.x * 8;
;     const float* MOD = (const float*)(a.ws + WS_MOD) + (size_t)layer * 9 * 6144;
;     const float* g = (which ? a.in[7] : a.in[6]) + layer * 1024;
;     bf16_t* XN = (bf16_t*)(a.ws + WS_XN);
;     const int c0 = which ? 3 : 0;
;     for (int chunk = gw; chunk < M_ / 32; chunk += NGW) { const int row = chunk * 32, b = row / SEQ; const float* mb = MOD + (size_t)b * 6144;
;         norm_rows(x + (size_t)row * 1024, 32, g, mb + (c0 + 1) * 1024, mb + c0 * 1024, XN + (size_t)row * 1024, lane); }
;     if (with_ctx) { const float* mb = MOD + (size_t)8 * 6144;
;         for (int row = gw; row < MCTX; row += NGW) norm_rows(a.in[2] + (size_t)row * 1024, 1, g, mb + (c0 + 1) * 1024, mb + c0 * 1024, XN + (size_t)(M_ + row) * 1024, lane); }
; }
.LBB0_313:
	s_lshr_b32 s97, s3, 1
	s_cmp_lt_i32 s2, s97
	s_cbranch_scc1 .LBB0_321
	s_sub_i32 s95, s2, s97
	v_lshl_add_u32 v32, s95, 3, v133
	s_movk_i32 s0, 0x800
	v_cmp_gt_i32_e32 vcc, s0, v32
	s_and_saveexec_b64 s[8:9], vcc
	s_cbranch_execz .LBB0_320
	v_mbcnt_lo_u32_b32 v1, -1, 0
	v_mbcnt_hi_u32_b32 v1, -1, v1
	v_and_b32_e32 v3, 64, v1
	v_add_u32_e32 v3, 64, v3
	v_xor_b32_e32 v5, 1, v1
	v_cmp_lt_i32_e32 vcc, v5, v3
	v_mov_b32_e32 v37, 0
	v_lshlrev_b32_e32 v38, 3, v153
	v_cndmask_b32_e32 v5, v1, v5, vcc
	v_lshlrev_b32_e32 v80, 2, v5
	v_xor_b32_e32 v5, 2, v1
	v_cmp_lt_i32_e32 vcc, v5, v3
	v_mov_b32_e32 v39, v37
	v_lshlrev_b32_e32 v0, 2, v153
	v_cndmask_b32_e32 v5, v1, v5, vcc
	v_lshlrev_b32_e32 v81, 2, v5
	v_xor_b32_e32 v5, 4, v1
	v_cmp_lt_i32_e32 vcc, v5, v3
	v_lshlrev_b32_e32 v36, 4, v153
	v_lshl_add_u64 v[8:9], s[28:29], 0, v[38:39]
	v_cndmask_b32_e32 v5, v1, v5, vcc
	v_lshlrev_b32_e32 v82, 2, v5
	v_xor_b32_e32 v5, 8, v1
	v_cmp_lt_i32_e32 vcc, v5, v3
	s_mov_b64 s[0:1], 0x7601e00
	v_or_b32_e32 v2, 0x100, v0
	v_cndmask_b32_e32 v5, v1, v5, vcc
	v_lshlrev_b32_e32 v83, 2, v5
	v_xor_b32_e32 v5, 16, v1
	v_cmp_lt_i32_e32 vcc, v5, v3
	v_or_b32_e32 v4, 0x200, v0
	v_or_b32_e32 v6, 0x300, v0
	v_cndmask_b32_e32 v5, v1, v5, vcc
	v_lshlrev_b32_e32 v84, 2, v5
	v_xor_b32_e32 v5, 32, v1
	v_cmp_lt_i32_e32 vcc, v5, v3
	v_lshl_add_u64 v[48:49], v[8:9], 0, s[0:1]
	v_lshl_add_u64 v[8:9], s[36:37], 0, v[36:37]
	v_cndmask_b32_e32 v1, v1, v5, vcc
	v_lshlrev_b32_e32 v85, 2, v1
	v_lshlrev_b32_e32 v1, 5, v133
	s_mov_b64 s[0:1], 0x3c00
	s_lshl_b32 s10, s97, 3
	v_lshl_add_u64 v[34:35], s[48:49], 0, v[36:37]
	v_lshl_add_u32 v50, s95, 8, v1
	s_lshl_b32 s11, s97, 8
	v_lshl_add_u64 v[52:53], v[8:9], 0, s[0:1]
	s_mov_b64 s[12:13], 0
	s_mov_b64 s[22:23], 0x1000
	v_lshlrev_b32_e32 v46, 2, v0
	v_mov_b32_e32 v47, v37
	v_lshlrev_b32_e32 v44, 2, v2
	v_mov_b32_e32 v45, v37
	v_lshlrev_b32_e32 v42, 2, v4
	v_mov_b32_e32 v43, v37
	v_lshlrev_b32_e32 v40, 2, v6
	v_mov_b32_e32 v41, v37
	s_movk_i32 s25, 0xf000
	s_mov_b32 s24, 0x3a800000
	s_mov_b32 s38, 0x358637bd
	s_mov_b32 s39, 0x800000
	s_mov_b64 s[42:43], 0x2000
	s_mov_b64 s[44:45], 0x4000
	s_movk_i32 s46, 0x7ff
	v_mov_b32_e32 v33, v32
